# P+2 merge loop unrolled by two with two iterations of loads in flight (counted vmcnt) and SGPR-base plus 32-bit offset addressing
# speedup vs baseline: 1.0029x; 1.0029x over previous
.LBB0_450:
	v_lshl_add_u32 v4, s62, 9, v149
	s_mov_b32 s10, 0x200000
	v_cmp_gt_i32_e32 vcc, s10, v4
	s_and_saveexec_b64 s[0:1], vcc
	v_readlane_b32 s8, v254, 11
	v_readlane_b32 s9, v254, 12
	s_cbranch_execz .LBB0_453
	s_add_u32 s2, s46, 0x11c00000
	s_addc_u32 s3, s47, 0
	s_add_u32 s36, s46, 0xbc00000
	s_addc_u32 s37, s47, 0
	s_add_u32 s38, s46, 0xdc00000
	s_addc_u32 s39, s47, 0
	s_add_u32 s40, s46, 0xfc00000
	s_addc_u32 s41, s47, 0
	s_add_u32 s46, s46, 0x13c00000
	v_lshlrev_b32_e32 v0, 3, v149
	s_addc_u32 s47, s47, 0
	v_lshl_add_u32 v5, s62, 12, v0
	s_mov_b64 s[62:63], 0
	s_add_u32 s14, s2, 0x100000
	s_addc_u32 s15, s3, 0
	s_add_u32 s16, s2, 0x200000
	s_addc_u32 s17, s3, 0
	v_add_u32_e32 v77, s8, v4
	s_mov_b32 s6, 0x1fffff
	v_lshrrev_b32_e32 v73, 6, v4
	v_bfe_u32 v74, v4, 3, 3
	v_and_b32_e32 v75, 7, v4
	v_lshlrev_b32_e32 v217, 5, v73
	v_lshl_or_b32 v217, v74, 2, v217
	v_lshlrev_b32_e32 v216, 10, v73
	v_lshl_or_b32 v216, v74, 7, v216
	v_lshl_or_b32 v216, v75, 4, v216
	global_load_dword v200, v217, s[2:3]
	global_load_dword v201, v217, s[14:15]
	global_load_dword v202, v217, s[16:17]
	global_load_dwordx4 v[204:207], v216, s[36:37]
	global_load_dwordx4 v[208:211], v216, s[38:39]
	global_load_dwordx4 v[212:215], v216, s[40:41]
	v_lshrrev_b32_e32 v73, 6, v77
	v_bfe_u32 v74, v77, 3, 3
	v_and_b32_e32 v75, 7, v77
	v_lshlrev_b32_e32 v197, 5, v73
	v_lshl_or_b32 v197, v74, 2, v197
	v_lshlrev_b32_e32 v196, 10, v73
	v_lshl_or_b32 v196, v74, 7, v196
	v_lshl_or_b32 v196, v75, 4, v196
	global_load_dword v220, v197, s[2:3]
	global_load_dword v221, v197, s[14:15]
	global_load_dword v222, v197, s[16:17]
	global_load_dwordx4 v[184:187], v196, s[36:37]
	global_load_dwordx4 v[188:191], v196, s[38:39]
	global_load_dwordx4 v[192:195], v196, s[40:41]
	s_waitcnt vmcnt(6)
.LBB0_452:
	v_max3_f32 v11, v200, v201, v202
	v_sub_f32_e32 v0, v200, v11
	v_cmp_gt_f32_e32 vcc, s97, v0
	s_nop 1
	v_cndmask_b32_e32 v2, 0, v233, vcc
	v_add_f32_e32 v0, v0, v2
	v_exp_f32_e32 v0, v0
	v_cndmask_b32_e32 v2, 0, v236, vcc
	v_ldexp_f32 v3, v0, v2
	v_sub_f32_e32 v0, v201, v11
	v_cmp_gt_f32_e32 vcc, s97, v0
	s_nop 1
	v_cndmask_b32_e32 v2, 0, v233, vcc
	v_add_f32_e32 v0, v0, v2
	v_exp_f32_e32 v0, v0
	v_cndmask_b32_e32 v2, 0, v236, vcc
	v_ldexp_f32 v2, v0, v2
	v_sub_f32_e32 v0, v202, v11
	v_cmp_gt_f32_e32 vcc, s97, v0
	s_nop 1
	v_cndmask_b32_e32 v8, 0, v233, vcc
	v_add_f32_e32 v0, v0, v8
	v_exp_f32_e32 v0, v0
	v_cndmask_b32_e32 v8, 0, v236, vcc
	v_ldexp_f32 v0, v0, v8
	v_add_f32_e32 v8, v3, v2
	v_add_f32_e32 v8, v0, v8
	v_div_scale_f32 v9, s[6:7], v8, v8, 1.0
	v_rcp_f32_e32 v11, v9
	s_mov_b32 s6, 0x1fffff
	v_fma_f32 v12, -v9, v11, 1.0
	v_fmac_f32_e32 v11, v12, v11
	v_div_scale_f32 v12, vcc, 1.0, v8, 1.0
	v_mul_f32_e32 v13, v12, v11
	v_fma_f32 v14, -v9, v13, v12
	v_fmac_f32_e32 v13, v14, v11
	v_fma_f32 v9, -v9, v13, v12
	v_div_fmas_f32 v9, v9, v11, v13
	v_div_fixup_f32 v18, v9, v8, 1.0
	v_pk_mul_f32 v[2:3], v[2:3], v[18:19] op_sel_hi:[1,0]
	v_mul_f32_e32 v0, v0, v18
	v_lshlrev_b32_e32 v22, 16, v204
	v_and_b32_e32 v19, 0xffff0000, v204
	v_and_b32_e32 v23, 0xffff0000, v208
	v_lshlrev_b32_e32 v18, 16, v208
	v_pk_mul_f32 v[22:23], v[2:3], v[22:23] op_sel:[1,0] op_sel_hi:[0,1]
	v_lshlrev_b32_e32 v24, 16, v212
	v_and_b32_e32 v25, 0xffff0000, v212
	v_pk_fma_f32 v[18:19], v[2:3], v[18:19], v[22:23]
	v_lshlrev_b32_e32 v10, 16, v205
	v_pk_fma_f32 v[18:19], v[0:1], v[24:25], v[18:19] op_sel_hi:[0,1,1]
	v_cvt_pk_bf16_f32 v6, v18, v19
	v_lshlrev_b32_e32 v18, 16, v209
	v_and_b32_e32 v11, 0xffff0000, v209
	v_and_b32_e32 v19, 0xffff0000, v205
	v_pk_mul_f32 v[10:11], v[2:3], v[10:11] op_sel:[1,0] op_sel_hi:[0,1]
	v_lshlrev_b32_e32 v14, 16, v213
	v_and_b32_e32 v15, 0xffff0000, v213
	v_pk_fma_f32 v[10:11], v[2:3], v[18:19], v[10:11]
	v_lshlrev_b32_e32 v18, 16, v214
	v_pk_fma_f32 v[10:11], v[0:1], v[14:15], v[10:11] op_sel_hi:[0,1,1]
	v_lshlrev_b32_e32 v14, 16, v206
	v_and_b32_e32 v15, 0xffff0000, v210
	v_cvt_pk_bf16_f32 v7, v10, v11
	v_lshlrev_b32_e32 v10, 16, v210
	v_and_b32_e32 v11, 0xffff0000, v206
	v_pk_mul_f32 v[14:15], v[2:3], v[14:15] op_sel:[1,0] op_sel_hi:[0,1]
	v_and_b32_e32 v19, 0xffff0000, v214
	v_pk_fma_f32 v[10:11], v[2:3], v[10:11], v[14:15]
	v_lshlrev_b32_e32 v12, 16, v207
	v_pk_fma_f32 v[10:11], v[0:1], v[18:19], v[10:11] op_sel_hi:[0,1,1]
	v_cvt_pk_bf16_f32 v8, v10, v11
	v_lshlrev_b32_e32 v10, 16, v211
	v_and_b32_e32 v13, 0xffff0000, v211
	v_and_b32_e32 v11, 0xffff0000, v207
	v_pk_mul_f32 v[12:13], v[2:3], v[12:13] op_sel:[1,0] op_sel_hi:[0,1]
	v_pk_fma_f32 v[2:3], v[2:3], v[10:11], v[12:13]
	v_lshlrev_b32_e32 v10, 16, v215
	v_and_b32_e32 v11, 0xffff0000, v215
	v_pk_fma_f32 v[2:3], v[0:1], v[10:11], v[2:3] op_sel_hi:[0,1,1]
	v_cvt_pk_bf16_f32 v9, v2, v3
	global_store_dwordx4 v216, v[6:9], s[46:47]
	v_lshl_add_u32 v4, s8, 1, v4
	v_cmp_lt_i32_e32 vcc, s6, v77
	v_lshrrev_b32_e32 v73, 6, v4
	v_bfe_u32 v74, v4, 3, 3
	v_and_b32_e32 v75, 7, v4
	v_lshlrev_b32_e32 v217, 5, v73
	v_lshl_or_b32 v217, v74, 2, v217
	v_lshlrev_b32_e32 v216, 10, v73
	v_lshl_or_b32 v216, v74, 7, v216
	v_lshl_or_b32 v216, v75, 4, v216
	global_load_dword v200, v217, s[2:3]
	global_load_dword v201, v217, s[14:15]
	global_load_dword v202, v217, s[16:17]
	global_load_dwordx4 v[204:207], v216, s[36:37]
	global_load_dwordx4 v[208:211], v216, s[38:39]
	global_load_dwordx4 v[212:215], v216, s[40:41]
	s_or_b64 s[62:63], vcc, s[62:63]
	s_andn2_b64 exec, exec, s[62:63]
	s_cbranch_execz .Lmerge_exit
	s_waitcnt vmcnt(7)
	v_max3_f32 v11, v220, v221, v222
	v_sub_f32_e32 v0, v220, v11
	v_cmp_gt_f32_e32 vcc, s97, v0
	s_nop 1
	v_cndmask_b32_e32 v2, 0, v233, vcc
	v_add_f32_e32 v0, v0, v2
	v_exp_f32_e32 v0, v0
	v_cndmask_b32_e32 v2, 0, v236, vcc
	v_ldexp_f32 v3, v0, v2
	v_sub_f32_e32 v0, v221, v11
	v_cmp_gt_f32_e32 vcc, s97, v0
	s_nop 1
	v_cndmask_b32_e32 v2, 0, v233, vcc
	v_add_f32_e32 v0, v0, v2
	v_exp_f32_e32 v0, v0
	v_cndmask_b32_e32 v2, 0, v236, vcc
	v_ldexp_f32 v2, v0, v2
	v_sub_f32_e32 v0, v222, v11
	v_cmp_gt_f32_e32 vcc, s97, v0
	s_nop 1
	v_cndmask_b32_e32 v8, 0, v233, vcc
	v_add_f32_e32 v0, v0, v8
	v_exp_f32_e32 v0, v0
	v_cndmask_b32_e32 v8, 0, v236, vcc
	v_ldexp_f32 v0, v0, v8
	v_add_f32_e32 v8, v3, v2
	v_add_f32_e32 v8, v0, v8
	v_div_scale_f32 v9, s[6:7], v8, v8, 1.0
	v_rcp_f32_e32 v11, v9
	s_mov_b32 s6, 0x1fffff
	v_fma_f32 v12, -v9, v11, 1.0
	v_fmac_f32_e32 v11, v12, v11
	v_div_scale_f32 v12, vcc, 1.0, v8, 1.0
	v_mul_f32_e32 v13, v12, v11
	v_fma_f32 v14, -v9, v13, v12
	v_fmac_f32_e32 v13, v14, v11
	v_fma_f32 v9, -v9, v13, v12
	v_div_fmas_f32 v9, v9, v11, v13
	v_div_fixup_f32 v18, v9, v8, 1.0
	v_pk_mul_f32 v[2:3], v[2:3], v[18:19] op_sel_hi:[1,0]
	v_mul_f32_e32 v0, v0, v18
	v_lshlrev_b32_e32 v22, 16, v184
	v_and_b32_e32 v19, 0xffff0000, v184
	v_and_b32_e32 v23, 0xffff0000, v188
	v_lshlrev_b32_e32 v18, 16, v188
	v_pk_mul_f32 v[22:23], v[2:3], v[22:23] op_sel:[1,0] op_sel_hi:[0,1]
	v_lshlrev_b32_e32 v24, 16, v192
	v_and_b32_e32 v25, 0xffff0000, v192
	v_pk_fma_f32 v[18:19], v[2:3], v[18:19], v[22:23]
	v_lshlrev_b32_e32 v10, 16, v185
	v_pk_fma_f32 v[18:19], v[0:1], v[24:25], v[18:19] op_sel_hi:[0,1,1]
	v_cvt_pk_bf16_f32 v6, v18, v19
	v_lshlrev_b32_e32 v18, 16, v189
	v_and_b32_e32 v11, 0xffff0000, v189
	v_and_b32_e32 v19, 0xffff0000, v185
	v_pk_mul_f32 v[10:11], v[2:3], v[10:11] op_sel:[1,0] op_sel_hi:[0,1]
	v_lshlrev_b32_e32 v14, 16, v193
	v_and_b32_e32 v15, 0xffff0000, v193
	v_pk_fma_f32 v[10:11], v[2:3], v[18:19], v[10:11]
	v_lshlrev_b32_e32 v18, 16, v194
	v_pk_fma_f32 v[10:11], v[0:1], v[14:15], v[10:11] op_sel_hi:[0,1,1]
	v_lshlrev_b32_e32 v14, 16, v186
	v_and_b32_e32 v15, 0xffff0000, v190
	v_cvt_pk_bf16_f32 v7, v10, v11
	v_lshlrev_b32_e32 v10, 16, v190
	v_and_b32_e32 v11, 0xffff0000, v186
	v_pk_mul_f32 v[14:15], v[2:3], v[14:15] op_sel:[1,0] op_sel_hi:[0,1]
	v_and_b32_e32 v19, 0xffff0000, v194
	v_pk_fma_f32 v[10:11], v[2:3], v[10:11], v[14:15]
	v_lshlrev_b32_e32 v12, 16, v187
	v_pk_fma_f32 v[10:11], v[0:1], v[18:19], v[10:11] op_sel_hi:[0,1,1]
	v_cvt_pk_bf16_f32 v8, v10, v11
	v_lshlrev_b32_e32 v10, 16, v191
	v_and_b32_e32 v13, 0xffff0000, v191
	v_and_b32_e32 v11, 0xffff0000, v187
	v_pk_mul_f32 v[12:13], v[2:3], v[12:13] op_sel:[1,0] op_sel_hi:[0,1]
	v_pk_fma_f32 v[2:3], v[2:3], v[10:11], v[12:13]
	v_lshlrev_b32_e32 v10, 16, v195
	v_and_b32_e32 v11, 0xffff0000, v195
	v_pk_fma_f32 v[2:3], v[0:1], v[10:11], v[2:3] op_sel_hi:[0,1,1]
	v_cvt_pk_bf16_f32 v9, v2, v3
	global_store_dwordx4 v196, v[6:9], s[46:47]
	v_lshl_add_u32 v77, s8, 1, v77
	v_cmp_lt_i32_e32 vcc, s6, v4
	v_lshrrev_b32_e32 v73, 6, v77
	v_bfe_u32 v74, v77, 3, 3
	v_and_b32_e32 v75, 7, v77
	v_lshlrev_b32_e32 v197, 5, v73
	v_lshl_or_b32 v197, v74, 2, v197
	v_lshlrev_b32_e32 v196, 10, v73
	v_lshl_or_b32 v196, v74, 7, v196
	v_lshl_or_b32 v196, v75, 4, v196
	global_load_dword v220, v197, s[2:3]
	global_load_dword v221, v197, s[14:15]
	global_load_dword v222, v197, s[16:17]
	global_load_dwordx4 v[184:187], v196, s[36:37]
	global_load_dwordx4 v[188:191], v196, s[38:39]
	global_load_dwordx4 v[192:195], v196, s[40:41]
	s_or_b64 s[62:63], vcc, s[62:63]
	s_waitcnt vmcnt(7)
	s_andn2_b64 exec, exec, s[62:63]
	s_cbranch_execnz .LBB0_452
.Lmerge_exit:
	s_waitcnt vmcnt(0)
.LBB0_453:
	s_or_b64 exec, exec, s[0:1]
	v_readlane_b32 s13, v255, 30
	s_add_i32 s8, s13, 5
	s_cmp_lt_i32 s8, s83
	s_cbranch_scc0 .LBB0_508
	s_waitcnt vmcnt(0)
	s_waitcnt vmcnt(0) lgkmcnt(0)
	s_barrier
	s_mov_b64 s[0:1], exec
	v_readlane_b32 s2, v254, 9
	v_readlane_b32 s3, v254, 10
	s_and_b64 s[2:3], s[0:1], s[2:3]
	s_mov_b64 exec, s[2:3]
	s_cbranch_execz .LBB0_507
	v_readlane_b32 s2, v255, 28
	s_waitcnt vmcnt(0) expcnt(0) lgkmcnt(0)
	s_nop 0
	v_mov_b32_e32 v0, s2
	ds_read_b32 v3, v0
	v_readlane_b32 s2, v255, 29
	s_waitcnt lgkmcnt(0)
	v_cmp_ne_u32_e32 vcc, 0, v3
	v_mov_b32_e32 v0, s2
	ds_read_b32 v2, v0
	s_cbranch_vccnz .LBB0_471
	s_mov_b32 s9, 1
	s_branch .LBB0_459

.Lepix_branch:
	s_branch .LBB0_521
	s_nop 0
	s_nop 0
	s_nop 0
	s_nop 0
	s_nop 0
	s_nop 0
	s_nop 0
	s_nop 0
	s_nop 0
	s_nop 0
	s_nop 0
	s_nop 0
	s_nop 0
	s_nop 0
	s_nop 0
